# KV window shift copy moved from P0 into P1 tile loop (one slice pair per wave per tile)
# baseline (speedup 1.0000x reference)
.LBB0_24:
	v_lshl_or_b32 v1, s4, 6, v2
	s_mov_b32 s6, 0xfe000
	v_cmp_gt_i32_e32 vcc, s6, v1
	s_and_saveexec_b64 s[8:9], vcc
	v_writelane_b32 v254, s36, 7
	s_load_dwordx2 s[52:53], s[0:1], 0xc0
	s_nop 0
	v_writelane_b32 v254, s37, 8
	v_writelane_b32 v254, s38, 9
	v_writelane_b32 v254, s39, 10
	v_writelane_b32 v254, s40, 11
	v_writelane_b32 v254, s41, 12
	v_writelane_b32 v254, s42, 13
	v_writelane_b32 v254, s43, 14
	v_writelane_b32 v254, s44, 15
	v_writelane_b32 v254, s45, 16
	v_writelane_b32 v254, s46, 17
	v_writelane_b32 v254, s47, 18
	v_writelane_b32 v254, s48, 19
	v_writelane_b32 v254, s49, 20
	v_writelane_b32 v254, s50, 21
	v_writelane_b32 v254, s51, 22
	s_nop 0
	v_readlane_b32 s50, v254, 0
.LBB0_32:
	s_or_b64 exec, exec, s[8:9]
	s_load_dwordx16 s[8:23], s[0:1], 0x40
	s_cmp_gt_i32 s4, 0x807f
	v_mbcnt_lo_u32_b32 v144, -1, 0
	s_waitcnt lgkmcnt(0)
	v_writelane_b32 v254, s8, 23
	s_nop 1
	v_writelane_b32 v254, s9, 24
	v_writelane_b32 v254, s10, 25
	v_writelane_b32 v254, s11, 26
	v_writelane_b32 v254, s12, 27
	v_writelane_b32 v254, s13, 28
	v_writelane_b32 v254, s14, 29
	v_writelane_b32 v254, s15, 30
	v_writelane_b32 v254, s16, 31
	v_writelane_b32 v254, s17, 32
	v_writelane_b32 v254, s18, 33
	v_writelane_b32 v254, s19, 34
	v_writelane_b32 v254, s20, 35
	v_writelane_b32 v254, s21, 36
	v_writelane_b32 v254, s22, 37
	v_writelane_b32 v254, s23, 38
	s_nop 0
	v_readlane_b32 s5, v254, 6
	s_cbranch_scc1 .LBB0_58
	v_mbcnt_hi_u32_b32 v3, -1, v144
	v_and_b32_e32 v1, 64, v3
	v_add_u32_e32 v4, 64, v1
	v_xor_b32_e32 v1, 1, v3
	v_cmp_lt_i32_e32 vcc, v1, v4
	v_xor_b32_e32 v5, 2, v3
	v_mov_b32_e32 v35, 0
	v_cndmask_b32_e32 v1, v3, v1, vcc
	v_cmp_lt_i32_e32 vcc, v5, v4
	s_add_u32 s16, s82, 0x40000
	s_mov_b64 s[0:1], 0x1d80000
	v_cndmask_b32_e32 v5, v3, v5, vcc
	v_lshlrev_b32_e32 v46, 2, v5
	v_xor_b32_e32 v5, 4, v3
	v_cmp_lt_i32_e32 vcc, v5, v4
	s_addc_u32 s17, s83, 0
	s_mov_b32 s13, 0
	v_cndmask_b32_e32 v5, v3, v5, vcc
	v_lshlrev_b32_e32 v47, 2, v5
	v_xor_b32_e32 v5, 8, v3
	v_cmp_lt_i32_e32 vcc, v5, v4
	v_lshlrev_b32_e32 v1, 2, v1
	v_mov_b32_e32 v51, 0x358637bd
	v_cndmask_b32_e32 v5, v3, v5, vcc
	v_lshlrev_b32_e32 v48, 2, v5
	v_xor_b32_e32 v5, 16, v3
	v_cmp_lt_i32_e32 vcc, v5, v4
	s_mov_b32 s18, 0xf800000
	v_mov_b32_e32 v52, 0x260
	v_cndmask_b32_e32 v5, v3, v5, vcc
	v_lshlrev_b32_e32 v49, 2, v5
	v_xor_b32_e32 v5, 32, v3
	v_cmp_lt_i32_e32 vcc, v5, v4
	s_nop 1
	v_cndmask_b32_e32 v3, v3, v5, vcc
	v_lshl_add_u64 v[4:5], s[82:83], 0, v[34:35]
	v_lshlrev_b32_e32 v50, 2, v3
	v_lshl_add_u64 v[36:37], v[4:5], 0, s[0:1]
	v_cmp_eq_u32_e64 s[0:1], 0, v2
	v_lshlrev_b32_e32 v34, 4, v2
	s_branch .LBB0_35

.LBB0_122:
	s_or_b64 exec, exec, s[0:1]
	v_readfirstlane_b32 s88, v228
	s_lshr_b32 s88, s88, 6
	s_lshl_b32 s89, s50, 3
	s_add_u32 s88, s88, s89
	s_lshl_b32 s89, s52, 3
	v_readlane_b32 s90, v254, 11
	v_readlane_b32 s91, v254, 12
	v_readlane_b32 s92, v254, 13
	v_readlane_b32 s93, v254, 14
	s_add_u32 s94, s80, 0x84c0000
	s_addc_u32 s95, s81, 0
	s_add_u32 s96, s80, 0x94c0000
	s_addc_u32 s97, s81, 0
	s_mov_b32 s99, 0
	v_and_b32_e32 v230, 63, v228
	v_lshlrev_b32_e32 v230, 4, v230
	s_add_u32 s0, s82, 0x1d80000
	s_addc_u32 s1, s83, 0
	v_writelane_b32 v254, s0, 39
	v_mov_b32_e32 v9, v228
	s_waitcnt lgkmcnt(0)
	v_writelane_b32 v254, s1, 40
	s_add_u32 s0, s82, 0x9e00000
	s_addc_u32 s1, s83, 0
	v_writelane_b32 v254, s0, 41
	s_barrier
	s_nop 0
	v_writelane_b32 v254, s1, 42
	v_writelane_b32 v254, s24, 43
	s_cmpk_gt_i32 s50, 0xaff
	v_readfirstlane_b32 s1, v9
	v_writelane_b32 v254, s25, 44
	s_cbranch_scc1 .LBB0_138
	v_lshlrev_b32_e32 v0, 4, v9
	v_add_u32_e32 v1, 0x2000, v0
	v_ashrrev_i32_e32 v2, 31, v1
	v_lshrrev_b32_e32 v2, 22, v2
	v_add_u32_e32 v2, v1, v2
	v_ashrrev_i32_e32 v8, 10, v2
	v_mul_i32_i24_e32 v2, 0x400, v8
	v_sub_u32_e32 v1, v1, v2
	v_lshrrev_b32_e32 v2, 4, v1
	v_bitop3_b32 v1, v2, v1, 32 bitop3:0x6c
	v_ashrrev_i32_e32 v2, 31, v1
	v_lshrrev_b32_e32 v2, 26, v2
	v_add_u32_e32 v2, v1, v2
	v_lshlrev_b32_e32 v3, 3, v8
	v_ashrrev_i32_e32 v10, 6, v2
	v_and_b32_e32 v3, -16, v3
	v_add_u32_e32 v3, v10, v3
	v_and_b32_e32 v4, 3, v10
	s_mov_b32 s0, 0x1fffe0
	v_lshrrev_b32_e32 v5, 2, v3
	v_lshlrev_b32_e32 v6, 1, v3
	v_and_b32_e32 v2, 0xc0, v2
	v_and_or_b32 v4, v3, s0, v4
	v_and_b32_e32 v5, 4, v5
	v_and_b32_e32 v6, 24, v6
	v_sub_u32_e32 v1, v1, v2
	v_mov_b32_e32 v2, 1
	v_or3_b32 v4, v4, v5, v6
	v_lshlrev_b32_e32 v5, 5, v8
	v_ashrrev_i16_sdwa v1, v2, sext(v1) dst_sel:DWORD dst_unused:UNUSED_PAD src0_sel:DWORD src1_sel:BYTE_0
	v_and_b32_e32 v5, 32, v5
	v_bfe_i32 v11, v1, 0, 16
	v_add_lshl_u32 v1, v5, v11, 1
	v_lshl_add_u32 v128, v4, 11, v1
	v_lshl_add_u32 v130, v3, 11, v1
	v_bfe_i32 v1, v9, 27, 1
	v_lshrrev_b32_e32 v1, 22, v1
	v_add_u32_e32 v1, v0, v1
	v_and_b32_e32 v1, 0xfffffc00, v1
	v_sub_u32_e32 v0, v0, v1
	v_lshrrev_b32_e32 v1, 4, v0
	v_bitop3_b32 v1, v1, v0, 32 bitop3:0x6c
	v_ashrrev_i32_e32 v0, 31, v0
	v_lshrrev_b32_e32 v0, 26, v0
	v_add_u32_e32 v0, v1, v0
	v_ashrrev_i32_e32 v12, 6, v0
	v_ashrrev_i32_e32 v0, 31, v9
	v_lshrrev_b32_e32 v0, 26, v0
	v_add_u32_e32 v0, v9, v0
	v_ashrrev_i32_e32 v13, 6, v0
	v_lshlrev_b32_e32 v0, 3, v13
	s_add_u32 s24, s82, 0x80000
	v_and_b32_e32 v0, -16, v0
	s_addc_u32 s25, s83, 0
	v_add_u32_e32 v0, v12, v0
	v_and_b32_e32 v3, 3, v12
	s_ashr_i32 s27, s50, 31
	v_and_or_b32 v3, v0, s0, v3
	s_lshr_b32 s0, s27, 29
	s_add_i32 s0, s50, s0
	s_ashr_i32 s4, s1, 6
	s_ashr_i32 s2, s0, 3
	s_and_b32 s0, s0, -8
	s_ashr_i32 s6, s1, 8
	s_lshl_b32 s26, s4, 10
	s_sub_i32 s0, s50, s0
	s_cmp_lt_i32 s0, 0
	s_movk_i32 s28, 0x161
	s_cselect_b32 s3, s28, 0x160
	s_mul_i32 s0, s0, s3
	s_add_i32 s0, s0, s2
	s_mul_hi_i32 s2, s0, 0x2e8ba2e9
	s_lshr_b32 s3, s2, 31
	s_ashr_i32 s2, s2, 5
	s_add_i32 s2, s2, s3
	s_lshl_b32 s3, s2, 3
	s_mulk_i32 s2, 0xb0
	s_sub_i32 s2, s0, s2
	s_sext_i32_i16 s0, s2
	s_bfe_u32 s0, s0, 0x3001c
	s_add_i32 s5, s2, s0
	s_sext_i32_i16 s0, s5
	s_and_b32 s5, s5, 0xfff8
	v_lshrrev_b32_e32 v4, 2, v0
	v_lshlrev_b32_e32 v5, 1, v0
	s_sub_i32 s2, s2, s5
	v_and_b32_e32 v4, 4, v4
	v_and_b32_e32 v5, 24, v5
	s_sext_i32_i16 s2, s2
	v_or3_b32 v3, v3, v4, v5
	v_mul_i32_i24_e32 v5, 64, v12
	s_lshr_b32 s0, s0, 3
	s_add_i32 s8, s3, s2
	v_sub_u32_e32 v1, v1, v5
	s_ashr_i32 s9, s8, 31
	s_bfe_i64 s[10:11], s[0:1], 0x100000
	v_lshlrev_b32_e32 v4, 5, v13
	v_ashrrev_i16_sdwa v1, v2, sext(v1) dst_sel:DWORD dst_unused:UNUSED_PAD src0_sel:DWORD src1_sel:BYTE_0
	s_lshl_b64 s[2:3], s[8:9], 19
	s_lshl_b64 s[10:11], s[10:11], 19
	v_and_b32_e32 v4, 32, v4
	v_bfe_i32 v14, v1, 0, 16
	s_add_u32 s20, s24, s10
	v_add_lshl_u32 v1, v4, v14, 1
	s_addc_u32 s21, s25, s11
	s_add_i32 s9, s26, 0
	v_lshl_add_u32 v132, v3, 11, v1
	s_add_i32 m0, s9, 0x10000
	v_lshl_add_u32 v134, v0, 11, v1
	global_load_lds_dwordx4 v132, s[20:21]
	s_add_i32 m0, s9, 0x12000
	s_add_u32 s10, s20, 0x40000
	global_load_lds_dwordx4 v128, s[20:21]
	s_addc_u32 s11, s21, 0
	s_add_i32 m0, s9, 0x14000
	v_mov_b32_e32 v133, 0
	global_load_lds_dwordx4 v132, s[10:11]
	s_add_i32 m0, s9, 0x16000
	v_mov_b32_e32 v129, v133
	global_load_lds_dwordx4 v128, s[10:11]
	v_readlane_b32 s10, v254, 39
	v_readlane_b32 s11, v254, 40
	s_add_u32 s18, s10, s2
	s_addc_u32 s19, s11, s3
	s_add_i32 s29, s9, 0x2000
	s_mov_b32 m0, s9
	s_add_u32 s2, s18, 0x40000
	global_load_lds_dwordx4 v134, s[18:19]
	s_mov_b32 m0, s29
	s_addc_u32 s3, s19, 0
	s_add_i32 s30, s9, 0x4000
	global_load_lds_dwordx4 v130, s[18:19]
	s_mov_b32 m0, s30
	s_add_i32 s31, s9, 0x6000
	global_load_lds_dwordx4 v134, s[2:3]
	s_mov_b32 m0, s31
	v_mov_b32_e32 v135, v133
	global_load_lds_dwordx4 v130, s[2:3]
	v_mov_b32_e32 v131, v133
	s_cmp_eq_u32 s6, 1
	s_mov_b32 s33, 0
	v_lshl_add_u64 v[6:7], s[20:21], 0, v[132:133]
	v_lshl_add_u64 v[4:5], s[20:21], 0, v[128:129]
	v_lshl_add_u64 v[0:1], s[18:19], 0, v[134:135]
	s_cselect_b64 s[2:3], -1, 0
	s_cmp_lg_u32 s6, 1
	v_lshl_add_u64 v[2:3], s[18:19], 0, v[130:131]
	s_cbranch_scc1 .LBB0_125
	s_barrier

.LBB0_131:
	ds_read_b128 v[152:155], v148
	ds_read_b128 v[156:159], v148 offset:1024
	ds_read_b128 v[160:163], v148 offset:2048
	ds_read_b128 v[164:167], v148 offset:3072
	ds_read_b128 v[168:171], v149
	ds_read_b128 v[172:175], v149 offset:1024
	ds_read_b128 v[176:179], v149 offset:2048
	ds_read_b128 v[180:183], v149 offset:3072
	s_add_u32 s20, s18, 0xfffc0080
	s_addc_u32 s21, s19, -1
	s_cmp_eq_u32 s46, 12
	s_cselect_b32 s23, s13, s21
	s_cselect_b32 s22, s42, s20
	s_cselect_b32 s21, s11, s45
	s_cselect_b32 s20, s43, s44
	s_add_i32 m0, s9, 0xc000
	ds_read_b128 v[184:187], v150
	ds_read_b128 v[188:191], v150 offset:1024
	ds_read_b128 v[192:195], v150 offset:2048
	ds_read_b128 v[196:199], v150 offset:3072
	ds_read_b128 v[200:203], v150 offset:4096
	ds_read_b128 v[204:207], v150 offset:5120
	ds_read_b128 v[208:211], v150 offset:6144
	ds_read_b128 v[212:215], v150 offset:7168
	global_load_lds_dwordx4 v136, s[18:19]
	s_add_i32 m0, s9, 0xe000
	s_nop 0
	global_load_lds_dwordx4 v138, s[18:19]
	s_waitcnt vmcnt(8)
	s_waitcnt lgkmcnt(0)
	s_barrier
	s_setprio 1
	s_waitcnt lgkmcnt(0)
	v_mfma_f32_16x16x32_bf16 v[124:127], v[152:155], v[184:187], v[124:127]
	v_mfma_f32_16x16x32_bf16 v[120:123], v[160:163], v[184:187], v[120:123]
	v_mfma_f32_16x16x32_bf16 v[116:119], v[152:155], v[192:195], v[116:119]
	v_mfma_f32_16x16x32_bf16 v[112:115], v[160:163], v[192:195], v[112:115]
	v_mfma_f32_16x16x32_bf16 v[100:103], v[152:155], v[200:203], v[100:103]
	v_mfma_f32_16x16x32_bf16 v[96:99], v[160:163], v[200:203], v[96:99]
	v_mfma_f32_16x16x32_bf16 v[84:87], v[152:155], v[208:211], v[84:87]
	v_mfma_f32_16x16x32_bf16 v[80:83], v[160:163], v[208:211], v[80:83]
	v_mfma_f32_16x16x32_bf16 v[124:127], v[156:159], v[188:191], v[124:127]
	v_mfma_f32_16x16x32_bf16 v[120:123], v[164:167], v[188:191], v[120:123]
	v_mfma_f32_16x16x32_bf16 v[116:119], v[156:159], v[196:199], v[116:119]
	v_mfma_f32_16x16x32_bf16 v[112:115], v[164:167], v[196:199], v[112:115]
	v_mfma_f32_16x16x32_bf16 v[100:103], v[156:159], v[204:207], v[100:103]
	v_mfma_f32_16x16x32_bf16 v[96:99], v[164:167], v[204:207], v[96:99]
	v_mfma_f32_16x16x32_bf16 v[84:87], v[156:159], v[212:215], v[84:87]
	v_mfma_f32_16x16x32_bf16 v[80:83], v[164:167], v[212:215], v[80:83]
	s_setprio 0
	s_setprio 1
	v_mfma_f32_16x16x32_bf16 v[108:111], v[168:171], v[184:187], v[108:111]
	v_mfma_f32_16x16x32_bf16 v[104:107], v[176:179], v[184:187], v[104:107]
	v_mfma_f32_16x16x32_bf16 v[92:95], v[168:171], v[192:195], v[92:95]
	v_mfma_f32_16x16x32_bf16 v[88:91], v[176:179], v[192:195], v[88:91]
	v_mfma_f32_16x16x32_bf16 v[76:79], v[168:171], v[200:203], v[76:79]
	v_mfma_f32_16x16x32_bf16 v[72:75], v[176:179], v[200:203], v[72:75]
	v_mfma_f32_16x16x32_bf16 v[68:71], v[168:171], v[208:211], v[68:71]
	v_mfma_f32_16x16x32_bf16 v[64:67], v[176:179], v[208:211], v[64:67]
	v_mfma_f32_16x16x32_bf16 v[108:111], v[172:175], v[188:191], v[108:111]
	v_mfma_f32_16x16x32_bf16 v[104:107], v[180:183], v[188:191], v[104:107]
	v_mfma_f32_16x16x32_bf16 v[92:95], v[172:175], v[196:199], v[92:95]
	v_mfma_f32_16x16x32_bf16 v[88:91], v[180:183], v[196:199], v[88:91]
	v_mfma_f32_16x16x32_bf16 v[76:79], v[172:175], v[204:207], v[76:79]
	v_mfma_f32_16x16x32_bf16 v[72:75], v[180:183], v[204:207], v[72:75]
	v_mfma_f32_16x16x32_bf16 v[68:71], v[172:175], v[212:215], v[68:71]
	v_mfma_f32_16x16x32_bf16 v[64:67], v[180:183], v[212:215], v[64:67]
	s_setprio 0
	s_barrier
	s_add_i32 s47, s38, s26
	s_mov_b32 m0, s47
	ds_read_b128 v[184:187], v150 offset:16384
	ds_read_b128 v[188:191], v150 offset:17408
	ds_read_b128 v[192:195], v150 offset:18432
	ds_read_b128 v[196:199], v150 offset:19456
	ds_read_b128 v[200:203], v150 offset:20480
	ds_read_b128 v[204:207], v150 offset:21504
	ds_read_b128 v[208:211], v150 offset:22528
	ds_read_b128 v[212:215], v150 offset:23552
	global_load_lds_dwordx4 v132, s[20:21]
	s_add_i32 m0, s47, 0x2000
	s_add_u32 s48, s20, 0x40000
	s_addc_u32 s49, s21, 0
	s_add_i32 s47, s39, s26
	global_load_lds_dwordx4 v128, s[20:21]
	s_mov_b32 m0, s47
	s_nop 0
	global_load_lds_dwordx4 v132, s[48:49]
	s_add_i32 m0, s47, 0x2000
	s_nop 0
	global_load_lds_dwordx4 v128, s[48:49]
	s_mov_b32 m0, s9
	s_nop 0
	global_load_lds_dwordx4 v134, s[22:23]
	s_mov_b32 m0, s29
	s_nop 0
	global_load_lds_dwordx4 v130, s[22:23]
	s_add_u32 s84, s20, s4
	s_addc_u32 s85, s21, s5
	s_add_u32 s86, s22, s4
	s_addc_u32 s87, s23, s5
	s_waitcnt vmcnt(8)
	s_waitcnt lgkmcnt(0)
	s_barrier
	s_setprio 1
	s_waitcnt lgkmcnt(0)
	v_mfma_f32_16x16x32_bf16 v[60:63], v[152:155], v[184:187], v[60:63]
	v_mfma_f32_16x16x32_bf16 v[56:59], v[160:163], v[184:187], v[56:59]
	v_mfma_f32_16x16x32_bf16 v[52:55], v[152:155], v[192:195], v[52:55]
	v_mfma_f32_16x16x32_bf16 v[48:51], v[160:163], v[192:195], v[48:51]
	v_mfma_f32_16x16x32_bf16 v[36:39], v[152:155], v[200:203], v[36:39]
	v_mfma_f32_16x16x32_bf16 v[32:35], v[160:163], v[200:203], v[32:35]
	v_mfma_f32_16x16x32_bf16 v[20:23], v[152:155], v[208:211], v[20:23]
	v_mfma_f32_16x16x32_bf16 v[16:19], v[160:163], v[208:211], v[16:19]
	v_mfma_f32_16x16x32_bf16 v[60:63], v[156:159], v[188:191], v[60:63]
	v_mfma_f32_16x16x32_bf16 v[56:59], v[164:167], v[188:191], v[56:59]
	v_mfma_f32_16x16x32_bf16 v[52:55], v[156:159], v[196:199], v[52:55]
	v_mfma_f32_16x16x32_bf16 v[48:51], v[164:167], v[196:199], v[48:51]
	v_mfma_f32_16x16x32_bf16 v[36:39], v[156:159], v[204:207], v[36:39]
	v_mfma_f32_16x16x32_bf16 v[32:35], v[164:167], v[204:207], v[32:35]
	v_mfma_f32_16x16x32_bf16 v[20:23], v[156:159], v[212:215], v[20:23]
	v_mfma_f32_16x16x32_bf16 v[16:19], v[164:167], v[212:215], v[16:19]
	s_setprio 0
	s_setprio 1
	v_mfma_f32_16x16x32_bf16 v[44:47], v[168:171], v[184:187], v[44:47]
	v_mfma_f32_16x16x32_bf16 v[40:43], v[176:179], v[184:187], v[40:43]
	v_mfma_f32_16x16x32_bf16 v[28:31], v[168:171], v[192:195], v[28:31]
	v_mfma_f32_16x16x32_bf16 v[24:27], v[176:179], v[192:195], v[24:27]
	v_mfma_f32_16x16x32_bf16 v[12:15], v[168:171], v[200:203], v[12:15]
	v_mfma_f32_16x16x32_bf16 v[8:11], v[176:179], v[200:203], v[8:11]
	v_mfma_f32_16x16x32_bf16 v[4:7], v[168:171], v[208:211], v[4:7]
	v_mfma_f32_16x16x32_bf16 v[0:3], v[176:179], v[208:211], v[0:3]
	v_mfma_f32_16x16x32_bf16 v[44:47], v[172:175], v[188:191], v[44:47]
	v_mfma_f32_16x16x32_bf16 v[40:43], v[180:183], v[188:191], v[40:43]
	v_mfma_f32_16x16x32_bf16 v[28:31], v[172:175], v[196:199], v[28:31]
	v_mfma_f32_16x16x32_bf16 v[24:27], v[180:183], v[196:199], v[24:27]
	v_mfma_f32_16x16x32_bf16 v[12:15], v[172:175], v[204:207], v[12:15]
	v_mfma_f32_16x16x32_bf16 v[8:11], v[180:183], v[204:207], v[8:11]
	v_mfma_f32_16x16x32_bf16 v[4:7], v[172:175], v[212:215], v[4:7]
	v_mfma_f32_16x16x32_bf16 v[0:3], v[180:183], v[212:215], v[0:3]
	s_setprio 0
	s_barrier
	s_add_i32 s47, 0, 0x18000
	v_add_u32_e32 v151, s47, v146
	s_add_i32 s48, 0, 0x1c000
	ds_read_b128 v[152:155], v151
	ds_read_b128 v[156:159], v151 offset:1024
	ds_read_b128 v[160:163], v151 offset:2048
	ds_read_b128 v[164:167], v151 offset:3072
	v_add_u32_e32 v151, s48, v146
	ds_read_b128 v[168:171], v151
	ds_read_b128 v[172:175], v151 offset:1024
	ds_read_b128 v[176:179], v151 offset:2048
	ds_read_b128 v[180:183], v151 offset:3072
	s_add_u32 s22, s22, 0x40000
	s_addc_u32 s23, s23, 0
	s_mov_b32 m0, s30
	ds_read_b128 v[184:187], v150 offset:32768
	ds_read_b128 v[188:191], v150 offset:33792
	ds_read_b128 v[192:195], v150 offset:34816
	ds_read_b128 v[196:199], v150 offset:35840
	ds_read_b128 v[200:203], v150 offset:36864
	ds_read_b128 v[204:207], v150 offset:37888
	ds_read_b128 v[208:211], v150 offset:38912
	ds_read_b128 v[212:215], v150 offset:39936
	global_load_lds_dwordx4 v134, s[22:23]
	s_mov_b32 m0, s31
	s_nop 0
	global_load_lds_dwordx4 v130, s[22:23]
	s_waitcnt vmcnt(8)
	s_waitcnt lgkmcnt(0)
	s_barrier
	s_setprio 1
	s_waitcnt lgkmcnt(0)
	v_mfma_f32_16x16x32_bf16 v[124:127], v[152:155], v[184:187], v[124:127]
	v_mfma_f32_16x16x32_bf16 v[120:123], v[160:163], v[184:187], v[120:123]
	v_mfma_f32_16x16x32_bf16 v[116:119], v[152:155], v[192:195], v[116:119]
	v_mfma_f32_16x16x32_bf16 v[112:115], v[160:163], v[192:195], v[112:115]
	v_mfma_f32_16x16x32_bf16 v[100:103], v[152:155], v[200:203], v[100:103]
	v_mfma_f32_16x16x32_bf16 v[96:99], v[160:163], v[200:203], v[96:99]
	v_mfma_f32_16x16x32_bf16 v[84:87], v[152:155], v[208:211], v[84:87]
	v_mfma_f32_16x16x32_bf16 v[80:83], v[160:163], v[208:211], v[80:83]
	v_mfma_f32_16x16x32_bf16 v[124:127], v[156:159], v[188:191], v[124:127]
	v_mfma_f32_16x16x32_bf16 v[120:123], v[164:167], v[188:191], v[120:123]
	v_mfma_f32_16x16x32_bf16 v[116:119], v[156:159], v[196:199], v[116:119]
	v_mfma_f32_16x16x32_bf16 v[112:115], v[164:167], v[196:199], v[112:115]
	v_mfma_f32_16x16x32_bf16 v[100:103], v[156:159], v[204:207], v[100:103]
	v_mfma_f32_16x16x32_bf16 v[96:99], v[164:167], v[204:207], v[96:99]
	v_mfma_f32_16x16x32_bf16 v[84:87], v[156:159], v[212:215], v[84:87]
	v_mfma_f32_16x16x32_bf16 v[80:83], v[164:167], v[212:215], v[80:83]
	s_setprio 0
	s_setprio 1
	v_mfma_f32_16x16x32_bf16 v[108:111], v[168:171], v[184:187], v[108:111]
	v_mfma_f32_16x16x32_bf16 v[104:107], v[176:179], v[184:187], v[104:107]
	v_mfma_f32_16x16x32_bf16 v[92:95], v[168:171], v[192:195], v[92:95]
	v_mfma_f32_16x16x32_bf16 v[88:91], v[176:179], v[192:195], v[88:91]
	v_mfma_f32_16x16x32_bf16 v[76:79], v[168:171], v[200:203], v[76:79]
	v_mfma_f32_16x16x32_bf16 v[72:75], v[176:179], v[200:203], v[72:75]
	v_mfma_f32_16x16x32_bf16 v[68:71], v[168:171], v[208:211], v[68:71]
	v_mfma_f32_16x16x32_bf16 v[64:67], v[176:179], v[208:211], v[64:67]
	v_mfma_f32_16x16x32_bf16 v[108:111], v[172:175], v[188:191], v[108:111]
	v_mfma_f32_16x16x32_bf16 v[104:107], v[180:183], v[188:191], v[104:107]
	v_mfma_f32_16x16x32_bf16 v[92:95], v[172:175], v[196:199], v[92:95]
	v_mfma_f32_16x16x32_bf16 v[88:91], v[180:183], v[196:199], v[88:91]
	v_mfma_f32_16x16x32_bf16 v[76:79], v[172:175], v[204:207], v[76:79]
	v_mfma_f32_16x16x32_bf16 v[72:75], v[180:183], v[204:207], v[72:75]
	v_mfma_f32_16x16x32_bf16 v[68:71], v[172:175], v[212:215], v[68:71]
	v_mfma_f32_16x16x32_bf16 v[64:67], v[180:183], v[212:215], v[64:67]
	s_setprio 0
	s_barrier
	s_add_i32 s22, s47, s26
	s_mov_b32 m0, s22
	ds_read_b128 v[184:187], v150 offset:49152
	ds_read_b128 v[188:191], v150 offset:50176
	ds_read_b128 v[192:195], v150 offset:51200
	ds_read_b128 v[196:199], v150 offset:52224
	ds_read_b128 v[200:203], v150 offset:53248
	ds_read_b128 v[204:207], v150 offset:54272
	ds_read_b128 v[208:211], v150 offset:55296
	ds_read_b128 v[212:215], v150 offset:56320
	global_load_lds_dwordx4 v132, s[84:85]
	s_add_i32 m0, s22, 0x2000
	s_add_u32 s20, s20, 0x40080
	s_addc_u32 s21, s21, 0
	s_add_i32 s22, s48, s26
	global_load_lds_dwordx4 v128, s[84:85]
	s_mov_b32 m0, s22
	s_nop 0
	global_load_lds_dwordx4 v132, s[20:21]
	s_add_i32 m0, s22, 0x2000
	s_nop 0
	global_load_lds_dwordx4 v128, s[20:21]
	s_mov_b32 m0, s34
	s_nop 0
	global_load_lds_dwordx4 v134, s[86:87]
	s_mov_b32 m0, s35
	s_nop 0
	global_load_lds_dwordx4 v130, s[86:87]
	s_waitcnt vmcnt(8)
	s_waitcnt lgkmcnt(0)
	s_barrier
	s_setprio 1
	s_waitcnt lgkmcnt(0)
	v_mfma_f32_16x16x32_bf16 v[60:63], v[152:155], v[184:187], v[60:63]
	v_mfma_f32_16x16x32_bf16 v[56:59], v[160:163], v[184:187], v[56:59]
	v_mfma_f32_16x16x32_bf16 v[52:55], v[152:155], v[192:195], v[52:55]
	v_mfma_f32_16x16x32_bf16 v[48:51], v[160:163], v[192:195], v[48:51]
	v_mfma_f32_16x16x32_bf16 v[36:39], v[152:155], v[200:203], v[36:39]
	v_mfma_f32_16x16x32_bf16 v[32:35], v[160:163], v[200:203], v[32:35]
	v_mfma_f32_16x16x32_bf16 v[20:23], v[152:155], v[208:211], v[20:23]
	v_mfma_f32_16x16x32_bf16 v[16:19], v[160:163], v[208:211], v[16:19]
	v_mfma_f32_16x16x32_bf16 v[60:63], v[156:159], v[188:191], v[60:63]
	v_mfma_f32_16x16x32_bf16 v[56:59], v[164:167], v[188:191], v[56:59]
	v_mfma_f32_16x16x32_bf16 v[52:55], v[156:159], v[196:199], v[52:55]
	v_mfma_f32_16x16x32_bf16 v[48:51], v[164:167], v[196:199], v[48:51]
	v_mfma_f32_16x16x32_bf16 v[36:39], v[156:159], v[204:207], v[36:39]
	v_mfma_f32_16x16x32_bf16 v[32:35], v[164:167], v[204:207], v[32:35]
	v_mfma_f32_16x16x32_bf16 v[20:23], v[156:159], v[212:215], v[20:23]
	v_mfma_f32_16x16x32_bf16 v[16:19], v[164:167], v[212:215], v[16:19]
	s_setprio 0
	s_setprio 1
	v_mfma_f32_16x16x32_bf16 v[44:47], v[168:171], v[184:187], v[44:47]
	v_mfma_f32_16x16x32_bf16 v[40:43], v[176:179], v[184:187], v[40:43]
	v_mfma_f32_16x16x32_bf16 v[28:31], v[168:171], v[192:195], v[28:31]
	v_mfma_f32_16x16x32_bf16 v[24:27], v[176:179], v[192:195], v[24:27]
	v_mfma_f32_16x16x32_bf16 v[12:15], v[168:171], v[200:203], v[12:15]
	v_mfma_f32_16x16x32_bf16 v[8:11], v[176:179], v[200:203], v[8:11]
	v_mfma_f32_16x16x32_bf16 v[4:7], v[168:171], v[208:211], v[4:7]
	v_mfma_f32_16x16x32_bf16 v[0:3], v[176:179], v[208:211], v[0:3]
	v_mfma_f32_16x16x32_bf16 v[44:47], v[172:175], v[188:191], v[44:47]
	v_mfma_f32_16x16x32_bf16 v[40:43], v[180:183], v[188:191], v[40:43]
	v_mfma_f32_16x16x32_bf16 v[28:31], v[172:175], v[196:199], v[28:31]
	v_mfma_f32_16x16x32_bf16 v[24:27], v[180:183], v[196:199], v[24:27]
	v_mfma_f32_16x16x32_bf16 v[12:15], v[172:175], v[204:207], v[12:15]
	v_mfma_f32_16x16x32_bf16 v[8:11], v[180:183], v[204:207], v[8:11]
	v_mfma_f32_16x16x32_bf16 v[4:7], v[172:175], v[212:215], v[4:7]
	v_mfma_f32_16x16x32_bf16 v[0:3], v[180:183], v[212:215], v[0:3]
	s_setprio 0
	s_barrier
	s_add_i32 s46, s46, 2
	s_add_u32 s18, s18, 0x100
	s_addc_u32 s19, s19, 0
	s_add_u32 s44, s44, 0x100
	s_addc_u32 s45, s45, 0
	s_cmp_gt_u32 s46, 13
	s_cbranch_scc0 .LBB0_131
	s_cmp_eq_u32 s99, 0
	s_cbranch_scc1 .LKV_P1_a
	global_store_dwordx4 v232, v[216:219], s[94:95]
	global_store_dwordx4 v232, v[220:223], s[96:97]
.LKV_P1_a:
	s_mov_b32 s99, 0
	s_cmp_ge_u32 s88, 0x3f80
	s_cbranch_scc1 .LKV_P1_b
	s_mul_i32 s98, s88, 0x8103
	s_lshr_b32 s98, s98, 22
	s_add_u32 s98, s98, s88
	s_lshl_b32 s98, s98, 10
	v_add_u32_e32 v231, s98, v230
	v_mov_b32_e32 v232, v231
	global_load_dwordx4 v[216:219], v231, s[90:91] offset:1024
	global_load_dwordx4 v[220:223], v231, s[92:93] offset:1024
	s_mov_b32 s99, 1
	s_add_u32 s88, s88, s89
.LKV_P1_b:
	s_and_b64 vcc, exec, s[6:7]
	s_cbranch_vccz .LBB0_134
	s_barrier
.LBB0_134:
	v_readlane_b32 s18, v254, 41
	v_lshl_add_u32 v151, s8, 8, v145
	v_lshl_or_b32 v152, s41, 8, v147
	v_readlane_b32 s19, v254, 42
	v_ashrrev_i32_e32 v153, 31, v152
	v_cvt_pk_bf16_f32 v68, v68, v69
	v_mov_b64_e32 v[154:155], s[18:19]
	v_cvt_pk_bf16_f32 v69, v70, v71
	v_cvt_pk_bf16_f32 v70, v64, v65
	v_add_u32_e32 v64, 0x80, v151
	v_mad_i64_i32 v[156:157], s[18:19], v151, s40, v[154:155]
	v_lshlrev_b64 v[152:153], 1, v[152:153]
	v_cvt_pk_bf16_f32 v108, v108, v109
	v_cvt_pk_bf16_f32 v109, v110, v111
	v_cvt_pk_bf16_f32 v110, v104, v105
	v_or_b32_e32 v104, 16, v151
	v_mad_i64_i32 v[64:65], s[18:19], v64, s40, v[154:155]
	v_cvt_pk_bf16_f32 v44, v44, v45
	v_cvt_pk_bf16_f32 v45, v46, v47
	v_cvt_pk_bf16_f32 v46, v40, v41
	v_add_u32_e32 v40, 0x90, v151
	v_lshl_add_u64 v[156:157], v[156:157], 0, v[152:153]
	v_cvt_pk_bf16_f32 v111, v106, v107
	v_mad_i64_i32 v[104:105], s[18:19], v104, s40, v[154:155]
	v_cvt_pk_bf16_f32 v92, v92, v93
	v_cvt_pk_bf16_f32 v93, v94, v95
	v_cvt_pk_bf16_f32 v94, v88, v89
	v_or_b32_e32 v88, 32, v151
	v_lshl_add_u64 v[64:65], v[64:65], 0, v[152:153]
	v_cvt_pk_bf16_f32 v47, v42, v43
	v_mad_i64_i32 v[40:41], s[18:19], v40, s40, v[154:155]
	v_cvt_pk_bf16_f32 v28, v28, v29
	v_cvt_pk_bf16_f32 v29, v30, v31
	v_cvt_pk_bf16_f32 v30, v24, v25
	v_add_u32_e32 v24, 0xa0, v151
	global_store_dwordx4 v[156:157], v[108:111], off offset:256
	v_cvt_pk_bf16_f32 v95, v90, v91
	v_mad_i64_i32 v[88:89], s[18:19], v88, s40, v[154:155]
	v_lshl_add_u64 v[108:109], v[104:105], 0, v[152:153]
	v_cvt_pk_bf16_f32 v76, v76, v77
	v_cvt_pk_bf16_f32 v77, v78, v79
	v_cvt_pk_bf16_f32 v78, v72, v73
	v_or_b32_e32 v72, 48, v151
	global_store_dwordx4 v[64:65], v[44:47], off offset:256
	v_cvt_pk_bf16_f32 v31, v26, v27
	v_mad_i64_i32 v[24:25], s[18:19], v24, s40, v[154:155]
	v_lshl_add_u64 v[44:45], v[40:41], 0, v[152:153]
	v_cvt_pk_bf16_f32 v12, v12, v13
	v_cvt_pk_bf16_f32 v13, v14, v15
	v_cvt_pk_bf16_f32 v14, v8, v9
	v_add_u32_e32 v8, 0xb0, v151
	global_store_dwordx4 v[108:109], v[92:95], off offset:256
	v_cvt_pk_bf16_f32 v79, v74, v75
	v_mad_i64_i32 v[72:73], s[18:19], v72, s40, v[154:155]
	v_lshl_add_u64 v[92:93], v[88:89], 0, v[152:153]
	global_store_dwordx4 v[44:45], v[28:31], off offset:256
	v_cvt_pk_bf16_f32 v15, v10, v11
	v_mad_i64_i32 v[8:9], s[18:19], v8, s40, v[154:155]
	v_lshl_add_u64 v[28:29], v[24:25], 0, v[152:153]
	v_cvt_pk_bf16_f32 v124, v124, v125
	v_cvt_pk_bf16_f32 v125, v126, v127
	v_cvt_pk_bf16_f32 v126, v120, v121
	v_cvt_pk_bf16_f32 v127, v122, v123
	v_cvt_pk_bf16_f32 v104, v116, v117
	v_cvt_pk_bf16_f32 v105, v118, v119
	v_cvt_pk_bf16_f32 v106, v112, v113
	v_cvt_pk_bf16_f32 v107, v114, v115
	v_cvt_pk_bf16_f32 v88, v100, v101
	v_cvt_pk_bf16_f32 v89, v102, v103
	v_cvt_pk_bf16_f32 v90, v96, v97
	v_cvt_pk_bf16_f32 v91, v98, v99
	global_store_dwordx4 v[92:93], v[76:79], off offset:256
	v_cvt_pk_bf16_f32 v74, v80, v81
	v_cvt_pk_bf16_f32 v75, v82, v83
	v_lshl_add_u64 v[76:77], v[72:73], 0, v[152:153]
	v_cvt_pk_bf16_f32 v72, v84, v85
	v_cvt_pk_bf16_f32 v73, v86, v87
	v_cvt_pk_bf16_f32 v71, v66, v67
	v_cvt_pk_bf16_f32 v60, v60, v61
	v_cvt_pk_bf16_f32 v61, v62, v63
	v_cvt_pk_bf16_f32 v62, v56, v57
	v_cvt_pk_bf16_f32 v63, v58, v59
	v_cvt_pk_bf16_f32 v40, v52, v53
	v_cvt_pk_bf16_f32 v41, v54, v55
	v_cvt_pk_bf16_f32 v42, v48, v49
	v_cvt_pk_bf16_f32 v43, v50, v51
	v_cvt_pk_bf16_f32 v24, v36, v37
	v_cvt_pk_bf16_f32 v25, v38, v39
	v_cvt_pk_bf16_f32 v26, v32, v33
	v_cvt_pk_bf16_f32 v27, v34, v35
	global_store_dwordx4 v[28:29], v[12:15], off offset:256
	v_cvt_pk_bf16_f32 v10, v16, v17
	v_cvt_pk_bf16_f32 v11, v18, v19
	v_lshl_add_u64 v[12:13], v[8:9], 0, v[152:153]
	v_cvt_pk_bf16_f32 v8, v20, v21
	v_cvt_pk_bf16_f32 v9, v22, v23
	v_cvt_pk_bf16_f32 v4, v4, v5
	v_cvt_pk_bf16_f32 v5, v6, v7
	v_cvt_pk_bf16_f32 v6, v0, v1
	v_cvt_pk_bf16_f32 v7, v2, v3
	s_andn2_b64 vcc, exec, s[0:1]
	s_mov_b64 s[0:1], -1
	global_store_dwordx4 v[156:157], v[124:127], off
	global_store_dwordx4 v[108:109], v[104:107], off
	global_store_dwordx4 v[92:93], v[88:91], off
	global_store_dwordx4 v[76:77], v[72:75], off
	global_store_dwordx4 v[76:77], v[68:71], off offset:256
	global_store_dwordx4 v[64:65], v[60:63], off
	global_store_dwordx4 v[44:45], v[40:43], off
	global_store_dwordx4 v[28:29], v[24:27], off
	global_store_dwordx4 v[12:13], v[8:11], off
	global_store_dwordx4 v[12:13], v[4:7], off offset:256
	s_cbranch_vccnz .LBB0_127
	s_andn2_b64 vcc, exec, s[2:3]
	s_cbranch_vccnz .LBB0_126
	s_barrier
	s_branch .LBB0_126

.LBB0_138:
	s_cmp_eq_u32 s99, 0
	s_cbranch_scc1 .LKV_P1_c
	s_waitcnt vmcnt(0)
	global_store_dwordx4 v232, v[216:219], s[94:95]
	global_store_dwordx4 v232, v[220:223], s[96:97]
.LKV_P1_c:
	s_cmp_ge_u32 s88, 0x3f80
	s_cbranch_scc1 .LKV_P1_d
	s_mul_i32 s98, s88, 0x8103
	s_lshr_b32 s98, s98, 22
	s_add_u32 s98, s98, s88
	s_lshl_b32 s98, s98, 10
	v_add_u32_e32 v231, s98, v230
	v_mov_b32_e32 v232, v231
	global_load_dwordx4 v[216:219], v231, s[90:91] offset:1024
	global_load_dwordx4 v[220:223], v231, s[92:93] offset:1024
	s_add_u32 s88, s88, s89
	s_waitcnt vmcnt(0)
	global_store_dwordx4 v232, v[216:219], s[94:95]
	global_store_dwordx4 v232, v[220:223], s[96:97]
	s_branch .LKV_P1_c
